# gates_phase: transposed butterfly wave reductions (8 gate columns reduced together, bias loaded once) instead of 36 serialized 6-hop reductions
# speedup vs baseline: 1.0455x; 1.0455x over previous
.LBB0_329:
	global_load_dwordx4 v[6:9], v[64:65], off
	s_waitcnt lgkmcnt(0)
	global_load_dwordx4 v[2:5], v[66:67], off
	global_load_dwordx4 v[10:13], v[68:69], off
	global_load_dwordx4 v[14:17], v[70:71], off
	v_lshl_add_u64 v[82:83], v[22:23], 0, s[8:9]
	s_mov_b64 s[18:19], 0x11200000
	s_mov_b32 s17, 0x11200000
	v_lshl_add_u64 v[94:95], v[82:83], 0, s[18:19]
	v_add_co_u32_e32 v98, vcc, s17, v82
	s_mov_b64 s[18:19], 0x11200040
	s_nop 0
	v_addc_co_u32_e32 v99, vcc, 0, v83, vcc
	v_lshl_add_u64 v[110:111], v[82:83], 0, s[18:19]
	global_load_dwordx4 v[82:85], v[98:99], off
	global_load_dwordx4 v[86:89], v[94:95], off offset:16
	global_load_dwordx4 v[90:93], v[94:95], off offset:32
	s_nop 0
	global_load_dwordx4 v[94:97], v[94:95], off offset:48
	s_nop 0
	global_load_dwordx4 v[98:101], v[98:99], off offset:64
	s_nop 0
	global_load_dwordx4 v[102:105], v[110:111], off offset:16
	global_load_dwordx4 v[106:109], v[110:111], off offset:48
	s_nop 0
	global_load_dwordx4 v[110:113], v[110:111], off offset:32
	s_add_u32 s8, s8, 0x2000
	s_addc_u32 s9, s9, 0
	v_lshl_add_u64 v[64:65], v[64:65], 0, s[10:11]
	v_lshl_add_u64 v[66:67], v[66:67], 0, s[10:11]
	v_lshl_add_u64 v[68:69], v[68:69], 0, s[10:11]
	v_lshl_add_u64 v[70:71], v[70:71], 0, s[10:11]
	s_cmp_eq_u32 s8, 0x10000
	s_waitcnt vmcnt(11)
	v_mov_b32_e32 v116, v7
	s_waitcnt vmcnt(10)
	v_mov_b32_e32 v117, v3
	v_mov_b32_e32 v120, v9
	v_mov_b32_e32 v121, v5
	s_waitcnt vmcnt(8)
	v_pk_mul_f32 v[124:125], v[16:17], v[16:17]
	v_pk_mul_f32 v[126:127], v[14:15], v[14:15]
	v_mov_b32_e32 v114, v6
	v_mov_b32_e32 v115, v2
	v_mov_b32_e32 v118, v8
	v_mov_b32_e32 v119, v4
	v_mul_f32_e32 v0, v11, v11
	v_mul_f32_e32 v122, v13, v13
	v_pk_mul_f32 v[116:117], v[116:117], v[116:117]
	v_pk_mul_f32 v[120:121], v[120:121], v[120:121]
	v_pk_mov_b32 v[138:139], v[126:127], v[124:125] op_sel:[1,0]
	v_mov_b32_e32 v127, v125
	v_pk_fma_f32 v[136:137], v[10:11], v[10:11], v[0:1] op_sel_hi:[1,1,0]
	v_pk_fma_f32 v[122:123], v[12:13], v[12:13], v[122:123] op_sel_hi:[1,1,0]
	v_pk_fma_f32 v[114:115], v[114:115], v[114:115], v[116:117]
	v_pk_fma_f32 v[116:117], v[118:119], v[118:119], v[120:121]
	v_pk_add_f32 v[118:119], v[138:139], v[126:127]
	s_waitcnt vmcnt(7)
	v_pk_fma_f32 v[74:75], v[6:7], v[82:83], v[74:75] op_sel_hi:[0,1,1]
	s_waitcnt vmcnt(6)
	v_pk_fma_f32 v[62:63], v[6:7], v[86:87], v[62:63] op_sel_hi:[0,1,1]
	v_pk_fma_f32 v[72:73], v[6:7], v[84:85], v[72:73] op_sel_hi:[0,1,1]
	v_pk_fma_f32 v[60:61], v[6:7], v[88:89], v[60:61] op_sel_hi:[0,1,1]
	v_pk_fma_f32 v[58:59], v[2:3], v[82:83], v[58:59] op_sel_hi:[0,1,1]
	v_pk_fma_f32 v[52:53], v[2:3], v[86:87], v[52:53] op_sel_hi:[0,1,1]
	v_pk_fma_f32 v[56:57], v[2:3], v[84:85], v[56:57] op_sel_hi:[0,1,1]
	v_pk_fma_f32 v[50:51], v[2:3], v[88:89], v[50:51] op_sel_hi:[0,1,1]
	v_pk_fma_f32 v[48:49], v[10:11], v[82:83], v[48:49] op_sel_hi:[0,1,1]
	v_pk_fma_f32 v[44:45], v[10:11], v[86:87], v[44:45] op_sel_hi:[0,1,1]
	v_pk_fma_f32 v[46:47], v[10:11], v[84:85], v[46:47] op_sel_hi:[0,1,1]
	v_pk_fma_f32 v[42:43], v[10:11], v[88:89], v[42:43] op_sel_hi:[0,1,1]
	v_pk_fma_f32 v[40:41], v[14:15], v[82:83], v[40:41] op_sel_hi:[0,1,1]
	v_pk_fma_f32 v[34:35], v[14:15], v[86:87], v[34:35] op_sel_hi:[0,1,1]
	v_pk_fma_f32 v[36:37], v[14:15], v[84:85], v[36:37] op_sel_hi:[0,1,1]
	v_pk_fma_f32 v[32:33], v[14:15], v[88:89], v[32:33] op_sel_hi:[0,1,1]
	v_mov_b32_e32 v137, v118
	v_mov_b32_e32 v123, v119
	s_waitcnt vmcnt(5)
	v_pk_fma_f32 v[74:75], v[6:7], v[90:91], v[74:75] op_sel:[1,0,0]
	s_waitcnt vmcnt(4)
	v_pk_fma_f32 v[62:63], v[6:7], v[94:95], v[62:63] op_sel:[1,0,0]
	v_pk_fma_f32 v[72:73], v[6:7], v[92:93], v[72:73] op_sel:[1,0,0]
	v_pk_fma_f32 v[6:7], v[6:7], v[96:97], v[60:61] op_sel:[1,0,0]
	v_pk_fma_f32 v[58:59], v[2:3], v[90:91], v[58:59] op_sel:[1,0,0]
	v_pk_fma_f32 v[52:53], v[2:3], v[94:95], v[52:53] op_sel:[1,0,0]
	v_pk_fma_f32 v[56:57], v[2:3], v[92:93], v[56:57] op_sel:[1,0,0]
	v_pk_fma_f32 v[2:3], v[2:3], v[96:97], v[50:51] op_sel:[1,0,0]
	v_pk_fma_f32 v[48:49], v[10:11], v[90:91], v[48:49] op_sel:[1,0,0]
	v_pk_fma_f32 v[44:45], v[10:11], v[94:95], v[44:45] op_sel:[1,0,0]
	v_pk_fma_f32 v[46:47], v[10:11], v[92:93], v[46:47] op_sel:[1,0,0]
	v_pk_fma_f32 v[10:11], v[10:11], v[96:97], v[42:43] op_sel:[1,0,0]
	v_pk_fma_f32 v[40:41], v[14:15], v[90:91], v[40:41] op_sel:[1,0,0]
	v_pk_fma_f32 v[34:35], v[14:15], v[94:95], v[34:35] op_sel:[1,0,0]
	v_pk_fma_f32 v[36:37], v[14:15], v[92:93], v[36:37] op_sel:[1,0,0]
	v_pk_fma_f32 v[14:15], v[14:15], v[96:97], v[32:33] op_sel:[1,0,0]
	v_mov_b32_e32 v128, v9
	v_mov_b32_e32 v130, v5
	v_mov_b32_e32 v132, v13
	v_mov_b32_e32 v134, v17
	v_pk_add_f32 v[82:83], v[114:115], v[116:117]
	v_pk_add_f32 v[32:33], v[136:137], v[122:123]
	s_waitcnt vmcnt(3)
	v_pk_fma_f32 v[42:43], v[8:9], v[98:99], v[74:75] op_sel_hi:[0,1,1]
	s_waitcnt vmcnt(2)
	v_pk_fma_f32 v[50:51], v[8:9], v[102:103], v[62:63] op_sel_hi:[0,1,1]
	v_pk_fma_f32 v[60:61], v[8:9], v[100:101], v[72:73] op_sel_hi:[0,1,1]
	v_pk_fma_f32 v[6:7], v[8:9], v[104:105], v[6:7] op_sel_hi:[0,1,1]
	v_pk_fma_f32 v[8:9], v[4:5], v[98:99], v[58:59] op_sel_hi:[0,1,1]
	v_pk_fma_f32 v[52:53], v[4:5], v[102:103], v[52:53] op_sel_hi:[0,1,1]
	v_pk_fma_f32 v[56:57], v[4:5], v[100:101], v[56:57] op_sel_hi:[0,1,1]
	v_pk_fma_f32 v[2:3], v[4:5], v[104:105], v[2:3] op_sel_hi:[0,1,1]
	v_pk_fma_f32 v[4:5], v[12:13], v[98:99], v[48:49] op_sel_hi:[0,1,1]
	v_pk_fma_f32 v[44:45], v[12:13], v[102:103], v[44:45] op_sel_hi:[0,1,1]
	v_pk_fma_f32 v[46:47], v[12:13], v[100:101], v[46:47] op_sel_hi:[0,1,1]
	v_pk_fma_f32 v[10:11], v[12:13], v[104:105], v[10:11] op_sel_hi:[0,1,1]
	v_pk_fma_f32 v[12:13], v[16:17], v[98:99], v[40:41] op_sel_hi:[0,1,1]
	v_pk_fma_f32 v[34:35], v[16:17], v[102:103], v[34:35] op_sel_hi:[0,1,1]
	v_pk_fma_f32 v[36:37], v[16:17], v[100:101], v[36:37] op_sel_hi:[0,1,1]
	v_pk_fma_f32 v[14:15], v[16:17], v[104:105], v[14:15] op_sel_hi:[0,1,1]
	v_pk_add_f32 v[54:55], v[54:55], v[82:83]
	v_pk_add_f32 v[38:39], v[38:39], v[32:33]
	s_waitcnt vmcnt(0)
	v_pk_fma_f32 v[74:75], v[128:129], v[110:111], v[42:43] op_sel_hi:[0,1,1]
	v_pk_fma_f32 v[62:63], v[128:129], v[106:107], v[50:51] op_sel_hi:[0,1,1]
	v_pk_fma_f32 v[72:73], v[128:129], v[112:113], v[60:61] op_sel_hi:[0,1,1]
	v_pk_fma_f32 v[60:61], v[128:129], v[108:109], v[6:7] op_sel_hi:[0,1,1]
	v_pk_fma_f32 v[58:59], v[130:131], v[110:111], v[8:9] op_sel_hi:[0,1,1]
	v_pk_fma_f32 v[52:53], v[130:131], v[106:107], v[52:53] op_sel_hi:[0,1,1]
	v_pk_fma_f32 v[56:57], v[130:131], v[112:113], v[56:57] op_sel_hi:[0,1,1]
	v_pk_fma_f32 v[50:51], v[130:131], v[108:109], v[2:3] op_sel_hi:[0,1,1]
	v_pk_fma_f32 v[48:49], v[132:133], v[110:111], v[4:5] op_sel_hi:[0,1,1]
	v_pk_fma_f32 v[44:45], v[132:133], v[106:107], v[44:45] op_sel_hi:[0,1,1]
	v_pk_fma_f32 v[46:47], v[132:133], v[112:113], v[46:47] op_sel_hi:[0,1,1]
	v_pk_fma_f32 v[42:43], v[132:133], v[108:109], v[10:11] op_sel_hi:[0,1,1]
	v_pk_fma_f32 v[40:41], v[134:135], v[110:111], v[12:13] op_sel_hi:[0,1,1]
	v_pk_fma_f32 v[34:35], v[134:135], v[106:107], v[34:35] op_sel_hi:[0,1,1]
	v_pk_fma_f32 v[36:37], v[134:135], v[112:113], v[36:37] op_sel_hi:[0,1,1]
	v_pk_fma_f32 v[32:33], v[134:135], v[108:109], v[14:15] op_sel_hi:[0,1,1]
	s_cbranch_scc0 .LBB0_329
	v_and_b32_e32 v0, 32, v226
	v_and_b32_e32 v2, 16, v226
	v_and_b32_e32 v3, 8, v226
	v_and_b32_e32 v4, 7, v226
	v_cmp_ne_u32_e64 s[40:41], 0, v0
	v_cmp_ne_u32_e64 s[42:43], 0, v2
	v_cmp_ne_u32_e64 s[44:45], 0, v3
	v_cmp_eq_u32_e64 s[46:47], 0, v4
	v_lshrrev_b32_e32 v5, 3, v226
	v_lshlrev_b32_e32 v5, 2, v5
	global_load_dword v6, v5, s[4:5]
	v_lshlrev_b32_e32 v7, 2, v226
	v_sub_u32_e32 v7, v7, v5
	v_sub_co_u32_e32 v8, vcc, v20, v7
	s_nop 1
	v_subb_co_u32_e32 v9, vcc, v21, v1, vcc
	v_lshlrev_b64 v[10:11], 5, v[18:19]
	v_lshl_add_u64 v[8:9], v[8:9], 0, v[10:11]
	v_cndmask_b32_e64 v82, v62, v74, s[40:41]
	v_cndmask_b32_e64 v74, v74, v62, s[40:41]
	v_cndmask_b32_e64 v83, v63, v75, s[40:41]
	v_cndmask_b32_e64 v75, v75, v63, s[40:41]
	v_cndmask_b32_e64 v84, v60, v72, s[40:41]
	v_cndmask_b32_e64 v72, v72, v60, s[40:41]
	v_cndmask_b32_e64 v85, v61, v73, s[40:41]
	v_cndmask_b32_e64 v73, v73, v61, s[40:41]
	v_cndmask_b32_e64 v86, v52, v58, s[40:41]
	v_cndmask_b32_e64 v58, v58, v52, s[40:41]
	v_cndmask_b32_e64 v87, v53, v59, s[40:41]
	v_cndmask_b32_e64 v59, v59, v53, s[40:41]
	v_cndmask_b32_e64 v88, v50, v56, s[40:41]
	v_cndmask_b32_e64 v56, v56, v50, s[40:41]
	v_cndmask_b32_e64 v89, v51, v57, s[40:41]
	v_cndmask_b32_e64 v57, v57, v51, s[40:41]
	ds_bpermute_b32 v82, v76, v82
	ds_bpermute_b32 v83, v76, v83
	ds_bpermute_b32 v84, v76, v84
	ds_bpermute_b32 v85, v76, v85
	ds_bpermute_b32 v86, v76, v86
	ds_bpermute_b32 v87, v76, v87
	ds_bpermute_b32 v88, v76, v88
	ds_bpermute_b32 v89, v76, v89
	ds_bpermute_b32 v90, v76, v54
	ds_bpermute_b32 v91, v76, v55
	s_waitcnt lgkmcnt(0)
	v_add_f32_e32 v74, v74, v82
	v_add_f32_e32 v75, v75, v83
	v_add_f32_e32 v72, v72, v84
	v_add_f32_e32 v73, v73, v85
	v_add_f32_e32 v58, v58, v86
	v_add_f32_e32 v59, v59, v87
	v_add_f32_e32 v56, v56, v88
	v_add_f32_e32 v57, v57, v89
	v_add_f32_e32 v54, v54, v90
	v_add_f32_e32 v55, v55, v91
	v_cndmask_b32_e64 v92, v72, v74, s[42:43]
	v_cndmask_b32_e64 v74, v74, v72, s[42:43]
	v_cndmask_b32_e64 v93, v73, v75, s[42:43]
	v_cndmask_b32_e64 v75, v75, v73, s[42:43]
	v_cndmask_b32_e64 v94, v56, v58, s[42:43]
	v_cndmask_b32_e64 v58, v58, v56, s[42:43]
	v_cndmask_b32_e64 v95, v57, v59, s[42:43]
	v_cndmask_b32_e64 v59, v59, v57, s[42:43]
	ds_bpermute_b32 v92, v77, v92
	ds_bpermute_b32 v93, v77, v93
	ds_bpermute_b32 v94, v77, v94
	ds_bpermute_b32 v95, v77, v95
	ds_bpermute_b32 v96, v77, v54
	ds_bpermute_b32 v97, v77, v55
	s_waitcnt lgkmcnt(0)
	v_add_f32_e32 v74, v74, v92
	v_add_f32_e32 v75, v75, v93
	v_add_f32_e32 v58, v58, v94
	v_add_f32_e32 v59, v59, v95
	v_add_f32_e32 v54, v54, v96
	v_add_f32_e32 v55, v55, v97
	v_cndmask_b32_e64 v98, v75, v74, s[44:45]
	v_cndmask_b32_e64 v74, v74, v75, s[44:45]
	v_cndmask_b32_e64 v99, v59, v58, s[44:45]
	v_cndmask_b32_e64 v58, v58, v59, s[44:45]
	ds_bpermute_b32 v98, v78, v98
	ds_bpermute_b32 v99, v78, v99
	ds_bpermute_b32 v100, v78, v54
	ds_bpermute_b32 v101, v78, v55
	s_waitcnt lgkmcnt(0)
	v_add_f32_e32 v74, v74, v98
	v_add_f32_e32 v58, v58, v99
	v_add_f32_e32 v54, v54, v100
	v_add_f32_e32 v55, v55, v101
	ds_bpermute_b32 v102, v79, v74
	ds_bpermute_b32 v103, v79, v54
	ds_bpermute_b32 v104, v79, v58
	ds_bpermute_b32 v105, v79, v55
	s_waitcnt lgkmcnt(0)
	v_add_f32_e32 v74, v74, v102
	v_add_f32_e32 v54, v54, v103
	v_add_f32_e32 v58, v58, v104
	v_add_f32_e32 v55, v55, v105
	ds_bpermute_b32 v106, v80, v74
	ds_bpermute_b32 v107, v80, v54
	ds_bpermute_b32 v108, v80, v58
	ds_bpermute_b32 v109, v80, v55
	s_waitcnt lgkmcnt(0)
	v_add_f32_e32 v74, v74, v106
	v_add_f32_e32 v54, v54, v107
	v_add_f32_e32 v58, v58, v108
	v_add_f32_e32 v55, v55, v109
	ds_bpermute_b32 v110, v81, v74
	ds_bpermute_b32 v111, v81, v54
	ds_bpermute_b32 v112, v81, v58
	ds_bpermute_b32 v113, v81, v55
	s_waitcnt lgkmcnt(0)
	v_add_f32_e32 v74, v74, v110
	v_add_f32_e32 v54, v54, v111
	v_add_f32_e32 v58, v58, v112
	v_add_f32_e32 v55, v55, v113
	v_cndmask_b32_e64 v82, v44, v48, s[40:41]
	v_cndmask_b32_e64 v48, v48, v44, s[40:41]
	v_cndmask_b32_e64 v83, v45, v49, s[40:41]
	v_cndmask_b32_e64 v49, v49, v45, s[40:41]
	v_cndmask_b32_e64 v84, v42, v46, s[40:41]
	v_cndmask_b32_e64 v46, v46, v42, s[40:41]
	v_cndmask_b32_e64 v85, v43, v47, s[40:41]
	v_cndmask_b32_e64 v47, v47, v43, s[40:41]
	v_cndmask_b32_e64 v86, v34, v40, s[40:41]
	v_cndmask_b32_e64 v40, v40, v34, s[40:41]
	v_cndmask_b32_e64 v87, v35, v41, s[40:41]
	v_cndmask_b32_e64 v41, v41, v35, s[40:41]
	v_cndmask_b32_e64 v88, v32, v36, s[40:41]
	v_cndmask_b32_e64 v36, v36, v32, s[40:41]
	v_cndmask_b32_e64 v89, v33, v37, s[40:41]
	v_cndmask_b32_e64 v37, v37, v33, s[40:41]
	ds_bpermute_b32 v82, v76, v82
	ds_bpermute_b32 v83, v76, v83
	ds_bpermute_b32 v84, v76, v84
	ds_bpermute_b32 v85, v76, v85
	ds_bpermute_b32 v86, v76, v86
	ds_bpermute_b32 v87, v76, v87
	ds_bpermute_b32 v88, v76, v88
	ds_bpermute_b32 v89, v76, v89
	ds_bpermute_b32 v90, v76, v38
	ds_bpermute_b32 v91, v76, v39
	s_waitcnt lgkmcnt(0)
	v_add_f32_e32 v48, v48, v82
	v_add_f32_e32 v49, v49, v83
	v_add_f32_e32 v46, v46, v84
	v_add_f32_e32 v47, v47, v85
	v_add_f32_e32 v40, v40, v86
	v_add_f32_e32 v41, v41, v87
	v_add_f32_e32 v36, v36, v88
	v_add_f32_e32 v37, v37, v89
	v_add_f32_e32 v38, v38, v90
	v_add_f32_e32 v39, v39, v91
	v_cndmask_b32_e64 v92, v46, v48, s[42:43]
	v_cndmask_b32_e64 v48, v48, v46, s[42:43]
	v_cndmask_b32_e64 v93, v47, v49, s[42:43]
	v_cndmask_b32_e64 v49, v49, v47, s[42:43]
	v_cndmask_b32_e64 v94, v36, v40, s[42:43]
	v_cndmask_b32_e64 v40, v40, v36, s[42:43]
	v_cndmask_b32_e64 v95, v37, v41, s[42:43]
	v_cndmask_b32_e64 v41, v41, v37, s[42:43]
	ds_bpermute_b32 v92, v77, v92
	ds_bpermute_b32 v93, v77, v93
	ds_bpermute_b32 v94, v77, v94
	ds_bpermute_b32 v95, v77, v95
	ds_bpermute_b32 v96, v77, v38
	ds_bpermute_b32 v97, v77, v39
	s_waitcnt lgkmcnt(0)
	v_add_f32_e32 v48, v48, v92
	v_add_f32_e32 v49, v49, v93
	v_add_f32_e32 v40, v40, v94
	v_add_f32_e32 v41, v41, v95
	v_add_f32_e32 v38, v38, v96
	v_add_f32_e32 v39, v39, v97
	v_cndmask_b32_e64 v98, v49, v48, s[44:45]
	v_cndmask_b32_e64 v48, v48, v49, s[44:45]
	v_cndmask_b32_e64 v99, v41, v40, s[44:45]
	v_cndmask_b32_e64 v40, v40, v41, s[44:45]
	ds_bpermute_b32 v98, v78, v98
	ds_bpermute_b32 v99, v78, v99
	ds_bpermute_b32 v100, v78, v38
	ds_bpermute_b32 v101, v78, v39
	s_waitcnt lgkmcnt(0)
	v_add_f32_e32 v48, v48, v98
	v_add_f32_e32 v40, v40, v99
	v_add_f32_e32 v38, v38, v100
	v_add_f32_e32 v39, v39, v101
	ds_bpermute_b32 v102, v79, v48
	ds_bpermute_b32 v103, v79, v38
	ds_bpermute_b32 v104, v79, v40
	ds_bpermute_b32 v105, v79, v39
	s_waitcnt lgkmcnt(0)
	v_add_f32_e32 v48, v48, v102
	v_add_f32_e32 v38, v38, v103
	v_add_f32_e32 v40, v40, v104
	v_add_f32_e32 v39, v39, v105
	ds_bpermute_b32 v106, v80, v48
	ds_bpermute_b32 v107, v80, v38
	ds_bpermute_b32 v108, v80, v40
	ds_bpermute_b32 v109, v80, v39
	s_waitcnt lgkmcnt(0)
	v_add_f32_e32 v48, v48, v106
	v_add_f32_e32 v38, v38, v107
	v_add_f32_e32 v40, v40, v108
	v_add_f32_e32 v39, v39, v109
	ds_bpermute_b32 v110, v81, v48
	ds_bpermute_b32 v111, v81, v38
	ds_bpermute_b32 v112, v81, v40
	ds_bpermute_b32 v113, v81, v39
	s_waitcnt lgkmcnt(0)
	v_add_f32_e32 v48, v48, v110
	v_add_f32_e32 v38, v38, v111
	v_add_f32_e32 v40, v40, v112
	v_add_f32_e32 v39, v39, v113
	s_waitcnt vmcnt(0)
	v_fmamk_f32 v0, v54, 0x3a000000, v210
	v_mul_f32_e32 v2, 0x4b800000, v0
	v_cmp_gt_f32_e32 vcc, s67, v0
	s_nop 1
	v_cndmask_b32_e32 v0, v0, v2, vcc
	v_rsq_f32_e32 v0, v0
	s_nop 0
	v_mul_f32_e32 v2, 0x45800000, v0
	v_cndmask_b32_e32 v0, v0, v2, vcc
	v_mov_b32_e32 v54, v6
	v_fmac_f32_e32 v54, v74, v0
	v_fmamk_f32 v0, v55, 0x3a000000, v210
	v_mul_f32_e32 v2, 0x4b800000, v0
	v_cmp_gt_f32_e32 vcc, s67, v0
	s_nop 1
	v_cndmask_b32_e32 v0, v0, v2, vcc
	v_rsq_f32_e32 v0, v0
	s_nop 0
	v_mul_f32_e32 v2, 0x45800000, v0
	v_cndmask_b32_e32 v0, v0, v2, vcc
	v_mov_b32_e32 v55, v6
	v_fmac_f32_e32 v55, v58, v0
	v_fmamk_f32 v0, v38, 0x3a000000, v210
	v_mul_f32_e32 v2, 0x4b800000, v0
	v_cmp_gt_f32_e32 vcc, s67, v0
	s_nop 1
	v_cndmask_b32_e32 v0, v0, v2, vcc
	v_rsq_f32_e32 v0, v0
	s_nop 0
	v_mul_f32_e32 v2, 0x45800000, v0
	v_cndmask_b32_e32 v0, v0, v2, vcc
	v_mov_b32_e32 v38, v6
	v_fmac_f32_e32 v38, v48, v0
	v_fmamk_f32 v0, v39, 0x3a000000, v210
	v_mul_f32_e32 v2, 0x4b800000, v0
	v_cmp_gt_f32_e32 vcc, s67, v0
	s_nop 1
	v_cndmask_b32_e32 v0, v0, v2, vcc
	v_rsq_f32_e32 v0, v0
	s_nop 0
	v_mul_f32_e32 v2, 0x45800000, v0
	v_cndmask_b32_e32 v0, v0, v2, vcc
	v_mov_b32_e32 v39, v6
	v_fmac_f32_e32 v39, v40, v0
	s_and_saveexec_b64 s[8:9], s[46:47]
	global_store_dword v[8:9], v54, off
	v_add_co_u32_e32 v10, vcc, 0x10000, v8
	s_nop 1
	v_addc_co_u32_e32 v11, vcc, 0, v9, vcc
	global_store_dword v[10:11], v55, off
	v_add_co_u32_e32 v10, vcc, 0x20000, v8
	s_nop 1
	v_addc_co_u32_e32 v11, vcc, 0, v9, vcc
	global_store_dword v[10:11], v38, off
	v_add_co_u32_e32 v10, vcc, 0x30000, v8
	s_nop 1
	v_addc_co_u32_e32 v11, vcc, 0, v9, vcc
	global_store_dword v[10:11], v39, off
	s_branch .LBB0_327
